# RG-LRU prompt tile loop: the eight conv-output LDS reads of the gate section issued once right after the barrier (no per-group LDS round trip)
# speedup vs baseline: 1.0035x; 1.0035x over previous
.LBB0_513:
	s_or_b64 exec, exec, s[26:27]
	s_waitcnt lgkmcnt(0)
	s_barrier
	ds_read_b128 v[12:15], v46
	s_waitcnt lgkmcnt(4)
	ds_read_b128 v[16:19], v46 offset:16
	ds_read_b128 v[20:23], v47
	ds_read_b128 v[24:27], v47 offset:16
	ds_read_b128 v[98:101], v43 offset:18432
	ds_read_b128 v[102:105], v43 offset:18448
	s_waitcnt lgkmcnt(1)
	v_pk_fma_f32 v[100:101], v[22:23], v[100:101], v[14:15]
	v_pk_fma_f32 v[98:99], v[20:21], v[98:99], v[12:13]
	s_waitcnt lgkmcnt(0)
	v_pk_fma_f32 v[104:105], v[26:27], v[104:105], v[18:19]
	v_pk_fma_f32 v[102:103], v[24:25], v[102:103], v[16:17]
	ds_read_b128 v[12:15], v47 offset:256
	ds_read_b128 v[16:19], v47 offset:272
	ds_read_b128 v[20:23], v43 offset:18688
	ds_read_b128 v[24:27], v43 offset:18704
	s_waitcnt lgkmcnt(1)
	v_pk_fma_f32 v[100:101], v[14:15], v[22:23], v[100:101]
	v_pk_fma_f32 v[98:99], v[12:13], v[20:21], v[98:99]
	s_waitcnt lgkmcnt(0)
	v_pk_fma_f32 v[104:105], v[18:19], v[26:27], v[104:105]
	v_pk_fma_f32 v[102:103], v[16:17], v[24:25], v[102:103]
	ds_read_b128 v[12:15], v47 offset:512
	ds_read_b128 v[16:19], v47 offset:528
	ds_read_b128 v[20:23], v43 offset:18944
	ds_read_b128 v[24:27], v43 offset:18960
	s_waitcnt lgkmcnt(1)
	v_pk_fma_f32 v[100:101], v[14:15], v[22:23], v[100:101]
	v_pk_fma_f32 v[98:99], v[12:13], v[20:21], v[98:99]
	s_waitcnt lgkmcnt(0)
	v_pk_fma_f32 v[104:105], v[18:19], v[26:27], v[104:105]
	v_pk_fma_f32 v[102:103], v[16:17], v[24:25], v[102:103]
	ds_read_b128 v[12:15], v47 offset:768
	ds_read_b128 v[16:19], v47 offset:784
	ds_read_b128 v[20:23], v43 offset:19200
	ds_read_b128 v[24:27], v43 offset:19216
	s_waitcnt lgkmcnt(1)
	v_pk_fma_f32 v[14:15], v[14:15], v[22:23], v[100:101]
	v_pk_fma_f32 v[12:13], v[12:13], v[20:21], v[98:99]
	s_waitcnt lgkmcnt(0)
	v_pk_fma_f32 v[18:19], v[18:19], v[26:27], v[104:105]
	v_pk_fma_f32 v[16:17], v[16:17], v[24:25], v[102:103]
	ds_write_b128 v96, v[12:15] offset:35584
	ds_write_b128 v96, v[16:19] offset:35600
	v_cvt_pk_bf16_f32 v12, v12, v13
	v_cvt_pk_bf16_f32 v13, v14, v15
	v_cvt_pk_bf16_f32 v14, v16, v17
	v_cvt_pk_bf16_f32 v15, v18, v19
	ds_write_b128 v92, v[12:15] offset:53248
	s_waitcnt lgkmcnt(0)
	s_barrier
	ds_read_b32 v125, v3 offset:35584
	ds_read_b32 v126, v3 offset:35856
	ds_read_b32 v127, v3 offset:36128
	ds_read_b32 v128, v3 offset:36400
	ds_read_b32 v129, v3 offset:35648
	ds_read_b32 v130, v56 offset:35856
	ds_read_b32 v131, v56 offset:36128
	ds_read_b32 v132, v56 offset:36400
	ds_read_b128 v[16:19], v93 offset:53248
	ds_read_b128 v[12:15], v93 offset:53312
	ds_read_b128 v[20:23], v2
	ds_read_b128 v[24:27], v2 offset:9216
	s_waitcnt lgkmcnt(1)
	v_mfma_f32_16x16x32_bf16 v[20:23], v[16:19], v[20:23], 0
	s_waitcnt lgkmcnt(0)
	v_mfma_f32_16x16x32_bf16 v[98:101], v[16:19], v[24:27], 0
	ds_read_b128 v[24:27], v2 offset:64
	ds_read_b128 v[102:105], v2 offset:9280
	s_waitcnt lgkmcnt(1)
	v_mfma_f32_16x16x32_bf16 v[24:27], v[12:15], v[24:27], v[20:23]
	s_waitcnt lgkmcnt(0)
	v_mfma_f32_16x16x32_bf16 v[20:23], v[12:15], v[102:105], v[98:101]
	s_waitcnt vmcnt(3)
	s_nop 4
	v_add_f32_e32 v24, v1, v24
	v_mul_f32_e32 v24, 0xbfb8aa3b, v24
	v_exp_f32_e32 v24, v24
	s_nop 0
	v_add_f32_e32 v24, 1.0, v24
	v_rcp_f32_e32 v24, v24
	s_waitcnt vmcnt(1)
	v_add_f32_e32 v20, v38, v20
	v_mul_f32_e32 v20, 0xbfb8aa3b, v20
	v_exp_f32_e32 v20, v20
	v_mul_f32_e32 v24, v41, v24
	v_exp_f32_e32 v24, v24
	v_add_f32_e32 v21, v38, v21
	v_add_f32_e32 v20, 1.0, v20
	v_rcp_f32_e32 v20, v20
	v_fma_f32 v97, -v24, v24, 1.0
	v_max_f32_e32 v97, 0, v97
	v_sqrt_f32_e32 v97, v97
	ds_write_b32 v3, v24 offset:62464
	v_mul_f32_e32 v21, 0xbfb8aa3b, v21
	v_mul_f32_e32 v20, v20, v97
	v_exp_f32_e32 v21, v21
	v_mul_f32_e32 v20, v125, v20
	ds_write_b32 v52, v20
	v_add_f32_e32 v20, v1, v25
	v_mul_f32_e32 v20, 0xbfb8aa3b, v20
	v_exp_f32_e32 v20, v20
	v_add_f32_e32 v21, 1.0, v21
	v_rcp_f32_e32 v21, v21
	v_add_f32_e32 v20, 1.0, v20
	v_rcp_f32_e32 v20, v20
	s_nop 0
	v_mul_f32_e32 v20, v41, v20
	v_exp_f32_e32 v20, v20
	ds_write_b32 v3, v20 offset:62736
	v_fma_f32 v24, -v20, v20, 1.0
	v_max_f32_e32 v24, 0, v24
	v_sqrt_f32_e32 v24, v24
	s_nop 0
	v_mul_f32_e32 v20, v21, v24
	v_mul_f32_e32 v20, v126, v20
	ds_write_b32 v53, v20
	v_add_f32_e32 v20, v1, v26
	v_mul_f32_e32 v20, 0xbfb8aa3b, v20
	v_exp_f32_e32 v20, v20
	v_add_f32_e32 v21, v38, v22
	v_mul_f32_e32 v21, 0xbfb8aa3b, v21
	v_exp_f32_e32 v21, v21
	v_add_f32_e32 v20, 1.0, v20
	v_rcp_f32_e32 v20, v20
	v_add_f32_e32 v21, 1.0, v21
	v_rcp_f32_e32 v21, v21
	v_mul_f32_e32 v20, v41, v20
	v_exp_f32_e32 v20, v20
	ds_write_b32 v3, v20 offset:63008
	v_fma_f32 v22, -v20, v20, 1.0
	v_max_f32_e32 v22, 0, v22
	v_sqrt_f32_e32 v22, v22
	s_nop 0
	v_mul_f32_e32 v20, v21, v22
	v_mul_f32_e32 v20, v127, v20
	ds_write_b32 v54, v20
	v_add_f32_e32 v20, v1, v27
	v_mul_f32_e32 v20, 0xbfb8aa3b, v20
	v_exp_f32_e32 v20, v20
	v_add_f32_e32 v21, v38, v23
	v_mul_f32_e32 v21, 0xbfb8aa3b, v21
	v_exp_f32_e32 v21, v21
	v_add_f32_e32 v20, 1.0, v20
	v_rcp_f32_e32 v20, v20
	v_add_f32_e32 v21, 1.0, v21
	v_rcp_f32_e32 v21, v21
	v_mul_f32_e32 v20, v41, v20
	v_exp_f32_e32 v20, v20
	ds_write_b32 v3, v20 offset:63280
	v_fma_f32 v22, -v20, v20, 1.0
	v_max_f32_e32 v22, 0, v22
	v_sqrt_f32_e32 v22, v22
	s_nop 0
	v_mul_f32_e32 v20, v21, v22
	v_mul_f32_e32 v20, v128, v20
	ds_write_b32 v55, v20
	ds_read_b128 v[20:23], v30
	ds_read_b128 v[24:27], v30 offset:9216
	s_waitcnt lgkmcnt(1)
	v_mfma_f32_16x16x32_bf16 v[20:23], v[16:19], v[20:23], 0
	s_waitcnt lgkmcnt(0)
	v_mfma_f32_16x16x32_bf16 v[16:19], v[16:19], v[24:27], 0
	ds_read_b128 v[24:27], v30 offset:64
	ds_read_b128 v[98:101], v30 offset:9280
	s_waitcnt lgkmcnt(1)
	v_mfma_f32_16x16x32_bf16 v[20:23], v[12:15], v[24:27], v[20:23]
	s_waitcnt lgkmcnt(0)
	v_mfma_f32_16x16x32_bf16 v[12:15], v[12:15], v[98:101], v[16:19]
	s_nop 5
	v_add_f32_e32 v16, v29, v20
	v_mul_f32_e32 v16, 0xbfb8aa3b, v16
	v_exp_f32_e32 v16, v16
	s_waitcnt vmcnt(0)
	v_add_f32_e32 v12, v39, v12
	v_mul_f32_e32 v12, 0xbfb8aa3b, v12
	v_exp_f32_e32 v12, v12
	v_add_f32_e32 v16, 1.0, v16
	v_rcp_f32_e32 v16, v16
	v_add_f32_e32 v13, v39, v13
	v_add_f32_e32 v12, 1.0, v12
	v_rcp_f32_e32 v12, v12
	v_mul_f32_e32 v16, v42, v16
	v_exp_f32_e32 v16, v16
	v_mul_f32_e32 v13, 0xbfb8aa3b, v13
	v_exp_f32_e32 v13, v13
	v_fma_f32 v17, -v16, v16, 1.0
	v_max_f32_e32 v17, 0, v17
	v_sqrt_f32_e32 v17, v17
	ds_write_b32 v3, v16 offset:62528
	v_add_f32_e32 v13, 1.0, v13
	v_mul_f32_e32 v12, v12, v17
	v_rcp_f32_e32 v13, v13
	v_mul_f32_e32 v12, v129, v12
	ds_write_b32 v31, v12
	v_add_f32_e32 v12, v29, v21
	v_mul_f32_e32 v12, 0xbfb8aa3b, v12
	v_exp_f32_e32 v12, v12
	s_nop 0
	v_add_f32_e32 v12, 1.0, v12
	v_rcp_f32_e32 v12, v12
	s_nop 0
	v_mul_f32_e32 v12, v42, v12
	v_exp_f32_e32 v12, v12
	ds_write_b32 v56, v12 offset:62736
	v_fma_f32 v16, -v12, v12, 1.0
	v_max_f32_e32 v16, 0, v16
	v_sqrt_f32_e32 v16, v16
	s_nop 0
	v_mul_f32_e32 v12, v13, v16
	v_mul_f32_e32 v12, v130, v12
	ds_write_b32 v57, v12
	v_add_f32_e32 v12, v29, v22
	v_mul_f32_e32 v12, 0xbfb8aa3b, v12
	v_exp_f32_e32 v12, v12
	v_add_f32_e32 v13, v39, v14
	v_mul_f32_e32 v13, 0xbfb8aa3b, v13
	v_exp_f32_e32 v13, v13
	v_add_f32_e32 v12, 1.0, v12
	v_rcp_f32_e32 v12, v12
	v_add_f32_e32 v13, 1.0, v13
	v_rcp_f32_e32 v13, v13
	v_mul_f32_e32 v12, v42, v12
	v_exp_f32_e32 v12, v12
	ds_write_b32 v56, v12 offset:63008
	v_fma_f32 v14, -v12, v12, 1.0
	v_max_f32_e32 v14, 0, v14
	v_sqrt_f32_e32 v14, v14
	s_nop 0
	v_mul_f32_e32 v12, v13, v14
	v_mul_f32_e32 v12, v131, v12
	ds_write_b32 v58, v12
	v_add_f32_e32 v12, v29, v23
	v_mul_f32_e32 v12, 0xbfb8aa3b, v12
	v_exp_f32_e32 v12, v12
	v_add_f32_e32 v13, v39, v15
	v_mul_f32_e32 v13, 0xbfb8aa3b, v13
	v_exp_f32_e32 v13, v13
	v_add_f32_e32 v12, 1.0, v12
	v_rcp_f32_e32 v12, v12
	v_add_f32_e32 v13, 1.0, v13
	v_rcp_f32_e32 v13, v13
	v_mul_f32_e32 v12, v42, v12
	v_exp_f32_e32 v12, v12
	ds_write_b32 v56, v12 offset:63280
	v_fma_f32 v14, -v12, v12, 1.0
	v_max_f32_e32 v14, 0, v14
	v_sqrt_f32_e32 v14, v14
	s_nop 0
	v_mul_f32_e32 v12, v13, v14
	v_mul_f32_e32 v12, v132, v12
	ds_write_b32 v59, v12
	v_mov_b32_e32 v12, 0
	s_and_saveexec_b64 s[26:27], s[2:3]
	ds_read_b32 v12, v48 offset:34816
	s_or_b64 exec, exec, s[26:27]
	s_waitcnt lgkmcnt(0)
	s_barrier
	s_and_saveexec_b64 s[26:27], s[2:3]
	s_cbranch_execz .LBB0_517
	s_waitcnt lgkmcnt(0)
	ds_write_b32 v49, v12 offset:18432
